# v95 with the P7 group stagger lengthened to 6 x s_sleep 127
# speedup vs baseline: 1.0026x; 1.0026x over previous
.LBB0_486:
	s_or_b64 exec, exec, s[4:5]
	s_bitcmp1_b32 s2, 0
	s_cbranch_scc0 .Lstg_skip
	s_movk_i32 s74, 6
